# GLA chunk loop: partial-sum LDS reads issued before the LDS store burst, 8-lane row-sum by DPP adds instead of ds_bpermute (on the 12472 split)
# baseline (speedup 1.0000x reference)
; #define LAS __attribute__((address_space(3)))
; __device__ __forceinline__ void p2b_gla_main(Frame& F) {
;     ...
;             bf16x8_t vf[2];
; #pragma unroll
;             for (int s = 0; s < 2; ++s) { const LAS unsigned char* vp = lds + L_V + (32 * s + 8 * g + q4) * VST + (16 * cw + 4 * p4) * 2; vf[s] = cat8(tr_read(vp), tr_read(vp + 4 * VST)); }
;             bf16x8_t sb[4];
; #pragma unroll
;             for (int s = 0; s < 4; ++s) { v4u t; t.x = cvtpk(S[2 * s][0], S[2 * s][1]); t.y = cvtpk(S[2 * s][2], S[2 * s][3]); t.z = cvtpk(S[2 * s + 1][0], S[2 * s + 1][1]); t.w = cvtpk(S[2 * s + 1][2], S[2 * s + 1][3]); sb[s] = __builtin_bit_cast(bf16x8_t, t); }
;             float gs[8];
; #pragma unroll
;             for (int j = 0; j < 4; ++j) { const unsigned wj = cgr[j]; const float x0 = bflo(wj), x1 = bfhi(wj);
;                 const unsigned wb_ = (j < 2) ? cgb.x : cgb.y; const int sh = 16 * (j & 1);
;                 const float b0 = ((float)((wb_ >> sh) & 0xffu) - 128.f) * 0.03125f, b1 = ((float)((wb_ >> (sh + 8)) & 0xffu) - 128.f) * 0.03125f;
;                 gs[2 * j] = gwv[2 * j] * x0 * __builtin_amdgcn_rcpf((1.0f + __builtin_amdgcn_exp2f(-1.4426950408889634f * x0)) * (1.0f + __builtin_amdgcn_exp2f(-1.4426950408889634f * b0)));
;                 gs[2 * j + 1] = gwv[2 * j + 1] * x1 * __builtin_amdgcn_rcpf((1.0f + __builtin_amdgcn_exp2f(-1.4426950408889634f * x1)) * (1.0f + __builtin_amdgcn_exp2f(-1.4426950408889634f * b1))); }
; #pragma unroll
;             for (int it = 0; it < 4; ++it) {
;                 f32x4 oa = {0.f, 0.f, 0.f, 0.f};
;                 { const bf16x8_t a = *(const LAS bf16x8_t*)(lds + L_ATT + (16 * it + c16) * AST + (32 * kh + 8 * g) * 2); oa = MFMA16(a, kh ? vf[1] : vf[0], oa); }
;                 const LAS unsigned char* qp = lds + L_QD + (16 * it + c16) * QST + (128 * kh) * 2 + g * 16;
; #pragma unroll
;                 for (int s = 0; s < 4; ++s) oa = MFMA16(*(const LAS bf16x8_t*)(qp + s * 64), sb[s], oa);
; #pragma unroll
;                 for (int r = 0; r < 4; ++r) *(LAS float*)(lds + L_OP + kh * 64 * OST + (16 * it + 4 * g + r) * OST + (16 * cw + c16) * 4) = oa[r];
;                 if (c + 1 < SEQ / GCHUNK) GLA_LOAD_QK(c + 1, it);
;             }
; #pragma unroll
;             for (int t = 0; t < 8; ++t) {
;                 const LAS unsigned char* kp = lds + L_KT + (128 * kh + 16 * t + c16) * KST + g * 16;
; #pragma unroll
.LBB0_549:
	s_or_b64 exec, exec, s[28:29]
	ds_read_b64_tr_b16 v[62:63], v181
	ds_read_b64_tr_b16 v[64:65], v181 offset:576
	ds_read_b64_tr_b16 v[90:91], v181 offset:4608
	ds_read_b64_tr_b16 v[92:93], v181 offset:5184
	ds_read_b128 v[66:69], v182
	ds_read_b128 v[78:81], v184
	ds_read_b128 v[82:85], v184 offset:64
	ds_read_b128 v[86:89], v184 offset:128
	s_waitcnt lgkmcnt(4)
	v_cndmask_b32_e64 v77, v93, v65, s[6:7]
	v_cndmask_b32_e64 v76, v92, v64, s[6:7]
	v_cndmask_b32_e64 v75, v91, v63, s[6:7]
	v_cndmask_b32_e64 v74, v90, v62, s[6:7]
	v_cvt_pk_bf16_f32 v58, v42, v43
	v_cvt_pk_bf16_f32 v59, v44, v45
	s_waitcnt lgkmcnt(3)
	v_mfma_f32_16x16x32_bf16 v[66:69], v[66:69], v[74:77], 0
	v_cvt_pk_bf16_f32 v60, v46, v47
	v_cvt_pk_bf16_f32 v61, v48, v49
	v_cvt_pk_bf16_f32 v70, v34, v35
	v_cvt_pk_bf16_f32 v71, v36, v37
	s_waitcnt lgkmcnt(2)
	v_mfma_f32_16x16x32_bf16 v[66:69], v[78:81], v[58:61], v[66:69]
	v_cvt_pk_bf16_f32 v72, v26, v27
	v_cvt_pk_bf16_f32 v73, v28, v29
	ds_read_b128 v[188:191], v184 offset:192
	v_cvt_pk_bf16_f32 v78, v30, v31
	s_waitcnt lgkmcnt(2)
	v_mfma_f32_16x16x32_bf16 v[66:69], v[82:85], v[70:73], v[66:69]
	v_cvt_pk_bf16_f32 v79, v32, v33
	v_cvt_pk_bf16_f32 v80, v38, v39
	v_cvt_pk_bf16_f32 v81, v40, v41
	v_cvt_pk_bf16_f32 v82, v18, v19
	v_cvt_pk_bf16_f32 v83, v20, v21
	s_waitcnt lgkmcnt(1)
	v_mfma_f32_16x16x32_bf16 v[66:69], v[86:89], v[78:81], v[66:69]
	v_cvt_pk_bf16_f32 v84, v22, v23
	v_cvt_pk_bf16_f32 v85, v24, v25
	v_add_u32_e32 v135, 0x2000, v185
	v_add_u32_e32 v137, 0x2400, v185
	s_waitcnt lgkmcnt(0)
	v_mfma_f32_16x16x32_bf16 v[66:69], v[188:191], v[82:85], v[66:69]
	s_nop 7
	ds_write2_b32 v185, v66, v67 offset1:68
	ds_write2_b32 v185, v68, v69 offset0:136 offset1:204
	ds_read_b128 v[66:69], v182 offset:2304
	ds_read_b128 v[86:89], v184 offset:8448
	s_waitcnt lgkmcnt(1)
	v_mfma_f32_16x16x32_bf16 v[66:69], v[66:69], v[74:77], 0
	ds_read_b128 v[188:191], v184 offset:8512
	v_add_u32_e32 v131, 0x3200, v185
	v_add_u32_e32 v133, 0x3400, v185
	s_waitcnt lgkmcnt(1)
	v_mfma_f32_16x16x32_bf16 v[66:69], v[86:89], v[58:61], v[66:69]
	ds_read_b128 v[86:89], v184 offset:8576
	v_add_u32_e32 v214, s34, v99
	s_waitcnt lgkmcnt(1)
	v_mfma_f32_16x16x32_bf16 v[66:69], v[188:191], v[70:73], v[66:69]
	v_add_u32_e32 v188, 0x1000, v185
	v_add_u32_e32 v189, 0x1200, v185
	s_waitcnt lgkmcnt(0)
	v_mfma_f32_16x16x32_bf16 v[66:69], v[86:89], v[78:81], v[66:69]
	ds_read_b128 v[86:89], v184 offset:8640
	s_waitcnt lgkmcnt(0)
	v_mfma_f32_16x16x32_bf16 v[66:69], v[86:89], v[82:85], v[66:69]
	s_nop 7
	ds_write2_b32 v188, v66, v67 offset0:64 offset1:132
	ds_write2_b32 v189, v68, v69 offset0:72 offset1:140
	ds_read_b128 v[66:69], v182 offset:4608
	ds_read_b128 v[86:89], v184 offset:16896
	s_waitcnt lgkmcnt(1)
	v_mfma_f32_16x16x32_bf16 v[66:69], v[66:69], v[74:77], 0
	ds_read_b128 v[190:193], v184 offset:16960
	s_waitcnt lgkmcnt(1)
	v_mfma_f32_16x16x32_bf16 v[66:69], v[86:89], v[58:61], v[66:69]
	ds_read_b128 v[86:89], v184 offset:17024
	s_waitcnt lgkmcnt(1)
	v_mfma_f32_16x16x32_bf16 v[66:69], v[190:193], v[70:73], v[66:69]
	v_lshl_add_u64 v[190:191], s[56:57], 0, v[146:147]
	s_waitcnt lgkmcnt(0)
	v_mfma_f32_16x16x32_bf16 v[66:69], v[86:89], v[78:81], v[66:69]
	ds_read_b128 v[86:89], v184 offset:17088
	s_waitcnt lgkmcnt(0)
	v_mfma_f32_16x16x32_bf16 v[66:69], v[86:89], v[82:85], v[66:69]
	s_nop 7
	ds_write2_b32 v135, v66, v67 offset0:128 offset1:196
	ds_write2_b32 v137, v68, v69 offset0:8 offset1:76
	ds_read_b128 v[66:69], v182 offset:6912
	ds_read_b128 v[86:89], v184 offset:25344
	s_waitcnt lgkmcnt(1)
	v_mfma_f32_16x16x32_bf16 v[66:69], v[66:69], v[74:77], 0
	ds_read_b128 v[74:77], v184 offset:25408
	s_waitcnt lgkmcnt(1)
	v_mfma_f32_16x16x32_bf16 v[58:61], v[86:89], v[58:61], v[66:69]
	v_lshl_add_u64 v[86:87], s[56:57], 0, v[148:149]
	v_add_co_u32_e32 v194, vcc, s70, v86
	s_nop 2
	ds_read_b128 v[66:69], v184 offset:25472
	s_waitcnt lgkmcnt(1)
	v_mfma_f32_16x16x32_bf16 v[58:61], v[74:77], v[70:73], v[58:61]
	v_addc_co_u32_e32 v195, vcc, 0, v87, vcc
	s_waitcnt lgkmcnt(0)
	v_mfma_f32_16x16x32_bf16 v[58:61], v[66:69], v[78:81], v[58:61]
	ds_read_b128 v[66:69], v184 offset:25536
	s_waitcnt lgkmcnt(0)
	v_mfma_f32_16x16x32_bf16 v[58:61], v[66:69], v[82:85], v[58:61]
	s_nop 7
	ds_write2_b32 v131, v58, v59 offset0:64 offset1:132
	ds_write2_b32 v133, v60, v61 offset0:72 offset1:140
	ds_read_b128 v[58:61], v163 offset:33792
	ds_read_b128 v[66:69], v164 offset:33792
	v_lshl_add_u64 v[82:83], s[56:57], 0, v[152:153]
	ds_read_b128 v[70:73], v163 offset:33856
	ds_read_b128 v[74:77], v165 offset:33792
	s_waitcnt lgkmcnt(3)
	v_mfma_f32_16x16x32_bf16 v[42:45], v[58:61], v[62:65], v[42:45]
	v_add_co_u32_e32 v202, vcc, s70, v82
	s_waitcnt lgkmcnt(2)
	v_mfma_f32_16x16x32_bf16 v[58:61], v[66:69], v[62:65], v[46:49]
	s_nop 2
	ds_read_b128 v[46:49], v166 offset:33792
	ds_read_b128 v[66:69], v165 offset:33856
	ds_read_b128 v[78:81], v167 offset:33792
	v_addc_co_u32_e32 v203, vcc, 0, v83, vcc
	s_waitcnt lgkmcnt(2)
	v_mfma_f32_16x16x32_bf16 v[82:85], v[46:49], v[62:65], v[26:29]
	v_add_co_u32_e32 v46, vcc, s71, v86
	s_nop 1
	v_addc_co_u32_e32 v47, vcc, 0, v87, vcc
	v_add_co_u32_e32 v218, vcc, s70, v190
	v_mfma_f32_16x16x32_bf16 v[34:37], v[74:77], v[62:65], v[34:37]
	s_nop 0
	v_addc_co_u32_e32 v219, vcc, 0, v191, vcc
	ds_read_b128 v[74:77], v168 offset:33792
	ds_read_b128 v[86:89], v167 offset:33856
	ds_read_b128 v[26:29], v164 offset:33856
	global_load_dwordx4 v[190:193], v[194:195], off offset:1024
	s_nop 0
	global_load_dwordx4 v[194:197], v[194:195], off offset:3072
	s_nop 0
	global_load_dwordx4 v[198:201], v[202:203], off offset:1024
	s_nop 0
	global_load_dwordx4 v[202:205], v[202:203], off offset:3072
	s_nop 0
	global_load_dwordx4 v[206:209], v[46:47], off offset:1024
	global_load_dwordx4 v[210:213], v[46:47], off offset:3072
	ds_read_b128 v[46:49], v214
	global_load_dwordx4 v[214:217], v[218:219], off offset:1024
	s_nop 0
	global_load_dwordx4 v[218:221], v[218:219], off offset:3072
	s_waitcnt lgkmcnt(4)
; #define LAS __attribute__((address_space(3)))
; #define MFMA16(a, b, c) __builtin_amdgcn_mfma_f32_16x16x32_bf16((a), (b), (c), 0, 0, 0)
; __device__ __forceinline__ void p2b_gla_main(Frame& F) {
;     ...
; #pragma unroll
;             for (int t = 0; t < 8; ++t) {
;                 const LAS unsigned char* kp = lds + L_KT + (128 * kh + 16 * t + c16) * KST + g * 16;
; #pragma unroll
;                 for (int s = 0; s < 2; ++s) S[t] = MFMA16(*(const LAS bf16x8_t*)(kp + s * 64), vf[s], S[t]);
;                 const f32x4 dc = *(const LAS f32x4*)(lds + L_DEC + (128 * kh + 16 * t + 4 * g) * 4);
;                 S[t] = S[t] * dc;
;             }
	v_mfma_f32_16x16x32_bf16 v[30:33], v[78:81], v[62:65], v[30:33]
	s_waitcnt lgkmcnt(3)
	v_mfma_f32_16x16x32_bf16 v[78:81], v[74:77], v[62:65], v[38:41]
	s_nop 2
	ds_read_b128 v[38:41], v166 offset:33856
	s_waitcnt lgkmcnt(2)
	v_mfma_f32_16x16x32_bf16 v[74:77], v[26:29], v[90:93], v[58:61]
	v_add_u32_e32 v26, s36, v99
	ds_read_b128 v[26:29], v26
	v_mfma_f32_16x16x32_bf16 v[34:37], v[66:69], v[90:93], v[34:37]
	ds_read_b128 v[58:61], v168 offset:33856
	ds_read_b128 v[66:69], v169 offset:33792
	v_mfma_f32_16x16x32_bf16 v[42:45], v[70:73], v[90:93], v[42:45]
	s_waitcnt lgkmcnt(3)
	v_mfma_f32_16x16x32_bf16 v[70:73], v[38:41], v[90:93], v[82:85]
	v_add_u32_e32 v38, s38, v99
	ds_read_b128 v[38:41], v38
	ds_read_b128 v[222:225], v169 offset:33856
	s_waitcnt lgkmcnt(3)
	v_mfma_f32_16x16x32_bf16 v[58:61], v[58:61], v[90:93], v[78:81]
	s_nop 2
	v_add_u32_e32 v78, s1, v99
	v_mfma_f32_16x16x32_bf16 v[30:33], v[86:89], v[90:93], v[30:33]
	ds_read_b128 v[86:89], v78
	ds_read_b128 v[226:229], v170 offset:33792
	s_waitcnt lgkmcnt(4)
	v_mfma_f32_16x16x32_bf16 v[18:21], v[66:69], v[62:65], v[18:21]
	v_add_u32_e32 v66, s35, v99
	ds_read_b128 v[82:85], v66
	ds_read_b128 v[230:233], v170 offset:33856
	v_add_u32_e32 v66, s37, v99
	s_waitcnt lgkmcnt(2)
	v_mfma_f32_16x16x32_bf16 v[62:65], v[226:229], v[62:65], v[22:25]
	ds_read_b128 v[78:81], v66
	s_nop 1
	v_add_u32_e32 v22, s40, v99
	ds_read_b128 v[22:25], v22
	v_add_u32_e32 v66, s39, v99
	ds_read_b128 v[66:69], v66
	v_mfma_f32_16x16x32_bf16 v[18:21], v[222:225], v[90:93], v[18:21]
	s_waitcnt lgkmcnt(0)
	s_barrier
; #define LAS __attribute__((address_space(3)))
;     __device__ __forceinline__ float* SSQG() const { return (float*)(ws + WS_SSQG); }
; #define GLA_TICK(sec) do { if (blockIdx.x == 0 && F.wave == 0) { const unsigned tn_ = (unsigned)__builtin_amdgcn_s_memrealtime(); if ((sec) == PROBE_KIND) F.MISC[60] += tn_ - F.MISC[61]; F.MISC[61] = tn_; } } while (0)
; #define GLA_TICK(sec) do { } while (0)
; __device__ __forceinline__ void p2b_gla_main(Frame& F) {
;     ...
;             __syncthreads();
;             GLA_TICK(7);
;             if (c + 1 < SEQ / GCHUNK) GLA_STORE();
;             { const int row = tid >> 3, cg = tid & 7;
;                 const LAS f32x4* o0 = (const LAS f32x4*)(lds + L_OP + row * OST + cg * 32); const LAS f32x4* o1 = (const LAS f32x4*)(lds + L_OP + 64 * OST + row * OST + cg * 32);
;                 const f32x4 a = o0[0] + o1[0], bq = o0[1] + o1[1];
;                 v4u wv; wv.x = cvtpk(a[0] * gs[0], a[1] * gs[1]); wv.y = cvtpk(a[2] * gs[2], a[3] * gs[3]); wv.z = cvtpk(bq[0] * gs[4], bq[1] * gs[5]); wv.w = cvtpk(bq[2] * gs[6], bq[3] * gs[7]);
;                 const size_t grow = (size_t)c * GCHUNK + row;
;                 *(v4u*)(go0 + grow * gpitch + cg * 8) = wv;
;                 float ss = (a[0] * a[0] + a[1] * a[1]) + (a[2] * a[2] + a[3] * a[3]) + (bq[0] * bq[0] + bq[1] * bq[1]) + (bq[2] * bq[2] + bq[3] * bq[3]);
;                 ss += __shfl_xor(ss, 1); ss += __shfl_xor(ss, 2); ss += __shfl_xor(ss, 4);
;                 if (cg == 0) F.SSQG()[((size_t)b * SEQ + grow) * 32 + h * 8 + vs] = ss; }
	v_mfma_f32_16x16x32_bf16 v[62:65], v[230:233], v[90:93], v[62:65]
	ds_read_b128 v[234:237], v187
	ds_read_b128 v[238:241], v186
	ds_read_b128 v[242:245], v186 offset:16
	ds_read_b128 v[246:249], v187 offset:16
	s_waitcnt vmcnt(7)
	ds_write_b128 v172, v[190:193]
	s_waitcnt vmcnt(6)
	ds_write_b128 v173, v[194:197] offset:33792
	s_waitcnt vmcnt(5)
	ds_write_b128 v174, v[198:201]
	s_waitcnt vmcnt(4)
	ds_write_b128 v175, v[202:205] offset:33792
	s_waitcnt vmcnt(3)
	ds_write_b128 v172, v[206:209] offset:16896
	s_waitcnt vmcnt(2)
	ds_write_b128 v176, v[210:213] offset:33792
	s_waitcnt vmcnt(1)
	ds_write_b128 v177, v[214:217]
	s_waitcnt vmcnt(0)
	ds_write_b128 v178, v[218:221] offset:33792
	ds_write_b128 v179, v[50:53]
	ds_write_b128 v180, v[54:57]
	s_and_saveexec_b64 s[28:29], s[4:5]
	ds_write_b32 v129, v127
	s_or_b64 exec, exec, s[28:29]
	v_add_u32_sdwa v50, v158, s65 dst_sel:DWORD dst_unused:UNUSED_PAD src0_sel:BYTE_0 src1_sel:DWORD
	v_cvt_f32_i32_e32 v50, v50
	v_add_u32_sdwa v51, v158, s65 dst_sel:DWORD dst_unused:UNUSED_PAD src0_sel:BYTE_1 src1_sel:DWORD
	v_cvt_f32_i32_e32 v51, v51
	v_lshlrev_b32_e32 v52, 16, v14
	v_mul_f32_e32 v50, 0x3d000000, v50
	v_mul_f32_e32 v50, 0xbfb8aa3b, v50
	v_and_b32_e32 v53, 0xffff0000, v14
	v_mul_f32_e32 v14, 0xbfb8aa3b, v52
	v_mul_f32_e32 v55, 0x3d000000, v51
	v_exp_f32_e32 v51, v50
	v_exp_f32_e32 v50, v14
	v_mul_f32_e32 v14, 0xbfb8aa3b, v53
	v_exp_f32_e32 v54, v14
	v_mul_f32_e32 v14, 0xbfb8aa3b, v55
	v_pk_add_f32 v[50:51], v[50:51], 1.0 op_sel_hi:[1,0]
	v_exp_f32_e32 v55, v14
	v_mul_f32_e32 v14, v50, v51
	v_rcp_f32_e32 v50, v14
	v_add_u32_sdwa v14, v158, s65 dst_sel:DWORD dst_unused:UNUSED_PAD src0_sel:BYTE_2 src1_sel:DWORD
	v_cvt_f32_i32_e32 v14, v14
	v_add_u32_sdwa v51, v158, s65 dst_sel:DWORD dst_unused:UNUSED_PAD src0_sel:BYTE_3 src1_sel:DWORD
	v_cvt_f32_i32_e32 v56, v51
	v_pk_add_f32 v[54:55], v[54:55], 1.0 op_sel_hi:[1,0]
	v_mul_f32_e32 v14, 0x3d000000, v14
	v_mul_f32_e32 v14, 0xbfb8aa3b, v14
	v_mul_f32_e32 v51, v54, v55
	v_exp_f32_e32 v55, v14
	v_lshlrev_b32_e32 v14, 16, v15
	v_mul_f32_e32 v54, 0xbfb8aa3b, v14
	v_mul_f32_e32 v57, 0x3d000000, v56
	v_and_b32_e32 v15, 0xffff0000, v15
	v_exp_f32_e32 v54, v54
	v_mul_f32_e32 v56, 0xbfb8aa3b, v15
	v_mul_f32_e32 v57, 0xbfb8aa3b, v57
	v_exp_f32_e32 v56, v56
	v_exp_f32_e32 v57, v57
	v_pk_add_f32 v[54:55], v[54:55], 1.0 op_sel_hi:[1,0]
	v_lshlrev_b32_e32 v192, 16, v16
	v_mul_f32_e32 v54, v54, v55
	v_rcp_f32_e32 v190, v54
	v_pk_add_f32 v[54:55], v[56:57], 1.0 op_sel_hi:[1,0]
	v_add_u32_sdwa v56, v159, s65 dst_sel:DWORD dst_unused:UNUSED_PAD src0_sel:BYTE_0 src1_sel:DWORD
	v_cvt_f32_i32_e32 v56, v56
	v_add_u32_sdwa v57, v159, s65 dst_sel:DWORD dst_unused:UNUSED_PAD src0_sel:BYTE_1 src1_sel:DWORD
	v_mul_f32_e32 v54, v54, v55
	v_cvt_f32_i32_e32 v57, v57
	v_rcp_f32_e32 v191, v54
	v_mul_f32_e32 v54, 0x3d000000, v56
	v_mul_f32_e32 v54, 0xbfb8aa3b, v54
	v_and_b32_e32 v193, 0xffff0000, v16
	v_mul_f32_e32 v16, 0xbfb8aa3b, v192
	v_exp_f32_e32 v55, v54
	v_exp_f32_e32 v54, v16
	v_mul_f32_e32 v57, 0x3d000000, v57
	v_mul_f32_e32 v16, 0xbfb8aa3b, v193
	v_exp_f32_e32 v56, v16
	v_mul_f32_e32 v16, 0xbfb8aa3b, v57
	v_exp_f32_e32 v57, v16
	v_pk_add_f32 v[54:55], v[54:55], 1.0 op_sel_hi:[1,0]
	v_lshlrev_b32_e32 v194, 16, v17
	v_mul_f32_e32 v16, v54, v55
	v_rcp_f32_e32 v158, v16
	v_add_u32_sdwa v16, v159, s65 dst_sel:DWORD dst_unused:UNUSED_PAD src0_sel:BYTE_2 src1_sel:DWORD
	v_cvt_f32_i32_e32 v16, v16
	v_pk_add_f32 v[54:55], v[56:57], 1.0 op_sel_hi:[1,0]
	v_add_u32_sdwa v56, v159, s65 dst_sel:DWORD dst_unused:UNUSED_PAD src0_sel:BYTE_3 src1_sel:DWORD
	v_cvt_f32_i32_e32 v56, v56
	v_mul_f32_e32 v16, 0x3d000000, v16
	v_mul_f32_e32 v16, 0xbfb8aa3b, v16
	v_mul_f32_e32 v54, v54, v55
	v_mul_f32_e32 v56, 0x3d000000, v56
	v_exp_f32_e32 v55, v16
	v_and_b32_e32 v195, 0xffff0000, v17
	v_mul_f32_e32 v16, 0xbfb8aa3b, v194
	v_rcp_f32_e32 v159, v54
	v_exp_f32_e32 v54, v16
	v_mul_f32_e32 v16, 0xbfb8aa3b, v195
	v_mul_f32_e32 v17, 0xbfb8aa3b, v56
	v_exp_f32_e32 v16, v16
	v_exp_f32_e32 v17, v17
	v_rcp_f32_e32 v51, v51
	v_pk_add_f32 v[54:55], v[54:55], 1.0 op_sel_hi:[1,0]
	v_pk_mul_f32 v[200:201], v[8:9], v[14:15]
	v_pk_add_f32 v[16:17], v[16:17], 1.0 op_sel_hi:[1,0]
	v_mul_f32_e32 v54, v54, v55
	v_mul_f32_e32 v16, v16, v17
	v_rcp_f32_e32 v197, v16
	v_pk_mul_f32 v[16:17], v[6:7], v[52:53]
	v_rcp_f32_e32 v196, v54
	v_pk_mul_f32 v[198:199], v[16:17], v[50:51]
	s_nop 0
	s_nop 0
	s_nop 0
	s_nop 0
	v_pk_mul_f32 v[190:191], v[200:201], v[190:191]
	v_pk_mul_f32 v[192:193], v[2:3], v[192:193]
	s_waitcnt lgkmcnt(10)
	v_pk_add_f32 v[16:17], v[240:241], v[236:237]
	v_pk_add_f32 v[14:15], v[238:239], v[234:235]
	v_mul_f32_e32 v51, v17, v17
	v_mul_f32_e32 v50, v15, v15
	s_nop 0
	v_pk_add_f32 v[52:53], v[242:243], v[246:247]
	v_fmac_f32_e32 v50, v14, v14
	v_fmac_f32_e32 v51, v16, v16
	v_add_f32_e32 v50, v50, v51
	v_mul_f32_e32 v51, v53, v53
	v_pk_add_f32 v[56:57], v[244:245], v[248:249]
	v_fmac_f32_e32 v51, v52, v52
	v_add_f32_e32 v50, v50, v51
	v_mul_f32_e32 v51, v57, v57
	v_fmac_f32_e32 v51, v56, v56
	v_add_f32_e32 v92, v51, v50
	s_nop 0
	v_pk_mul_f32 v[50:51], v[4:5], v[194:195]
	v_pk_mul_f32 v[14:15], v[198:199], v[14:15]
	v_pk_mul_f32 v[90:91], v[50:51], v[196:197]
	v_cvt_pk_bf16_f32 v50, v14, v15
	s_nop 0
	v_add_f32_dpp v93, v92, v92 quad_perm:[1,0,3,2] row_mask:0xf bank_mask:0xf
	s_nop 0
	v_pk_mul_f32 v[14:15], v[190:191], v[16:17]
	v_pk_mul_f32 v[54:55], v[192:193], v[158:159]
	v_cvt_pk_bf16_f32 v51, v14, v15
	v_pk_mul_f32 v[16:17], v[54:55], v[52:53]
	s_nop 0
	v_add_f32_dpp v92, v93, v93 quad_perm:[2,3,0,1] row_mask:0xf bank_mask:0xf
	s_nop 0
	v_cvt_pk_bf16_f32 v52, v16, v17
	v_pk_mul_f32 v[16:17], v[90:91], v[56:57]
	v_add_f32_dpp v14, v92, v92 row_half_mirror row_mask:0xf bank_mask:0xf
	s_nop 0
	v_cvt_pk_bf16_f32 v53, v16, v17
	global_store_dwordx4 v[142:143], v[50:53], off
	s_and_saveexec_b64 s[28:29], s[8:9]
	s_cbranch_execz .LBB0_553
	s_nop 0
	v_mov_b32_e32 v16, v14
	v_lshl_add_u64 v[14:15], s[56:57], 0, v[144:145]
	global_store_dword v[14:15], v16, off
